# P3 sample mLSTM: mo gate values prefetched at unit top instead of serialized loads in divergent branches
# baseline (speedup 1.0000x reference)
; __device__ __forceinline__ float sigmoidf_(float x) { return __builtin_amdgcn_rcpf(1.f + __expf(-x)); }
; __device__ __forceinline__ float bfv(bf16 v) { return __uint_as_float((unsigned)v << 16); }
; template <int MASK> __device__ __forceinline__ void phase3(const Args& a, LAS unsigned char* lds, int tid, int wave, int lane, int vcu, int G) {
;     ...
;             { const int b = ub >> 2, hd = ub & 3;
;                 __syncthreads();
;                 for (int i = tid; i < 3072; i += NTHREADS) { const int which = i >> 10, t = (i >> 7) & 7, d = i & 127; const size_t R = NP + 8 * b + t;
;                     QS[i] = which == 0 ? bfv(P1[R * P1W + C_MQ + hd * 128 + d]) : which == 1 ? bfv(P1[R * P1W + C_MK + hd * 128 + d]) : bfv(PT[(size_t)(R_MVT + hd * 128 + d) * MT + R]); }
;     ...
;                 for (int t = 0; t < 8; ++t) if ((t >> 1) == qt) {
;                     float num = SC[24 + t] * cq[t], den = SC[24 + t] * SC[128 + t];
; #pragma unroll
;                     for (int s = 0; s < 8; ++s) { const float w = SC[64 + t * 8 + s]; num += w * VS[s * 128 + dv]; den += w; }
;                     const float hh = num / fmaxf(fabsf(den), __expf(-SC[32 + t]));
;                     const size_t R = NP + 8 * b + t;
;                     const float hv = hh * sigmoidf_(bfv(P1[R * P1W + C_MO + hd * 128 + dv]));
.LBB0_700:
	s_and_b32 s37, s46, 3
	s_mov_b32 s4, s94
	s_lshl_b32 s94, s37, 7
	v_or_b32_e32 v2, s94, v108
	s_lshl_b32 s2, s46, 1
	v_mul_u32_u24_e32 v2, 0x4400, v2
	s_and_b32 s48, s2, -8
	v_lshlrev_b32_e32 v94, 1, v2
	s_lshl_b32 s52, s37, 8
	s_add_i32 s54, s48, 0x4000
	s_waitcnt lgkmcnt(0)
	v_lshl_add_u64 v[2:3], s[58:59], 0, v[94:95]
	v_lshl_add_u64 v[4:5], v[138:139], 0, s[52:53]
	v_lshl_add_u32 v188, v107, 1, s54
	v_lshlrev_b32_e32 v194, 1, v168
	v_add_u32_e32 v194, s52, v194
	v_mov_b32_e32 v195, 0
	v_lshl_add_u64 v[194:195], s[56:57], 0, v[194:195]
	v_mad_i64_i32 v[192:193], s[2:3], v188, s95, v[194:195]
	s_mov_b64 s[88:89], 0x1400
	global_load_ushort v190, v[192:193], off offset:3072
	v_lshl_add_u64 v[192:193], v[192:193], 0, s[88:89]
	global_load_ushort v191, v[192:193], off offset:3072
	v_add_u32_e32 v170, s54, v223
	v_add_u32_e32 v171, 4, v170
	s_mov_b64 s[88:89], 0x800
	v_mad_i64_i32 v[172:173], s[2:3], v170, s95, v[4:5]
	v_mad_i64_i32 v[174:175], s[2:3], v171, s95, v[4:5]
	global_load_ushort v182, v[172:173], off offset:2048
	global_load_ushort v183, v[174:175], off offset:2048
	v_lshl_add_u64 v[172:173], v[172:173], 0, s[88:89]
	v_lshl_add_u64 v[174:175], v[174:175], 0, s[88:89]
	global_load_ushort v184, v[172:173], off offset:2048
	global_load_ushort v185, v[174:175], off offset:2048
	v_mad_u64_u32 v[176:177], s[2:3], v170, 2, v[2:3]
	v_mad_u64_u32 v[178:179], s[2:3], v171, 2, v[2:3]
	global_load_ushort v186, v[176:177], off
	global_load_ushort v187, v[178:179], off
	s_barrier
	s_waitcnt vmcnt(5)
	v_lshlrev_b32_e32 v182, 16, v182
	ds_write_b32 v216, v182
	s_waitcnt vmcnt(4)
	v_lshlrev_b32_e32 v183, 16, v183
	ds_write_b32 v216, v183 offset:2048
	s_waitcnt vmcnt(3)
	v_lshlrev_b32_e32 v184, 16, v184
	ds_write_b32 v216, v184 offset:4096
	s_waitcnt vmcnt(2)
	v_lshlrev_b32_e32 v185, 16, v185
	ds_write_b32 v216, v185 offset:6144
	s_waitcnt vmcnt(1)
	v_lshlrev_b32_e32 v186, 16, v186
	ds_write_b32 v216, v186 offset:8192
	s_waitcnt vmcnt(0)
	v_lshlrev_b32_e32 v187, 16, v187
	ds_write_b32 v216, v187 offset:10240
	s_and_saveexec_b64 s[88:89], s[30:31]
	s_cbranch_execz .LBB0_712
; template <int MASK> __device__ __forceinline__ void phase3(const Args& a, LAS unsigned char* lds, int tid, int wave, int lane, int vcu, int G) {
;     ...
;                 if (tid == 0) {
;                     const float m0 = a.in[6][b * 4 + hd]; float F = 0.f, cm = m0; float bb[8];
; #pragma unroll
;                     for (int t = 0; t < 8; ++t) { const size_t R = NP + 8 * b + t; F += LF[R * 4 + hd]; bb[t] = IG[R * 4 + hd] - F; cm = fmaxf(cm, bb[t]);
;                         SC[t] = F; SC[8 + t] = bb[t]; SC[16 + t] = cm; SC[24 + t] = __expf(m0 - cm); SC[32 + t] = F + cm; }
; #pragma unroll
;                     for (int s = 0; s < 8; ++s) SC[40 + s] = __expf(bb[s] - cm);
;                     SC[48] = __expf(m0 - cm); SC[49] = F + cm;
;                 }
	s_ashr_i32 s47, s46, 31
	v_readlane_b32 s8, v253, 11
	s_lshl_b64 s[2:3], s[46:47], 2
	v_readlane_b32 s20, v253, 23
	v_readlane_b32 s21, v253, 24
	s_add_u32 s2, s20, s2
	s_addc_u32 s3, s21, s3
	s_ashr_i32 s55, s54, 31
	global_load_dword v30, v95, s[2:3]
	s_lshl_b64 s[2:3], s[54:55], 4
	s_lshl_b32 s47, s37, 2
	s_or_b32 s2, s2, s47
	s_add_u32 s68, s78, s2
	s_addc_u32 s69, s79, s3
	s_add_u32 s2, s74, s2
	s_addc_u32 s3, s75, s3
	s_ashr_i32 s49, s48, 31
	s_lshl_b64 s[90:91], s[48:49], 4
	s_or_b32 s47, s90, s47
	s_add_u32 s49, s47, 0x40010
	s_addc_u32 s52, s91, 0
	global_load_dword v8, v95, s[68:69]
	global_load_dword v3, v95, s[2:3]
	s_add_u32 s2, s78, s49
	s_addc_u32 s3, s79, s52
	global_load_dword v9, v95, s[2:3]
	s_add_u32 s2, s74, s49
	s_addc_u32 s3, s75, s52
	s_add_u32 s49, s47, 0x40020
	s_addc_u32 s52, s91, 0
	global_load_dword v4, v95, s[2:3]
	s_add_u32 s2, s78, s49
	s_addc_u32 s3, s79, s52
	global_load_dword v10, v95, s[2:3]
	s_add_u32 s2, s74, s49
	s_addc_u32 s3, s75, s52
	s_add_u32 s49, s47, 0x40030
	s_addc_u32 s52, s91, 0
	global_load_dword v5, v95, s[2:3]
	s_add_u32 s2, s78, s49
	s_addc_u32 s3, s79, s52
	global_load_dword v11, v95, s[2:3]
	s_add_u32 s2, s74, s49
	s_addc_u32 s3, s75, s52
	s_add_u32 s49, s47, 0x40040
	s_addc_u32 s52, s91, 0
	global_load_dword v6, v95, s[2:3]
	s_add_u32 s2, s78, s49
	s_addc_u32 s3, s79, s52
	global_load_dword v18, v95, s[2:3]
	s_add_u32 s2, s74, s49
	s_addc_u32 s3, s75, s52
	s_add_u32 s49, s47, 0x40050
	s_addc_u32 s52, s91, 0
	global_load_dword v7, v95, s[2:3]
	s_add_u32 s2, s78, s49
	s_addc_u32 s3, s79, s52
	global_load_dword v19, v95, s[2:3]
	s_add_u32 s2, s74, s49
	s_addc_u32 s3, s75, s52
	s_add_u32 s49, s47, 0x40060
	s_addc_u32 s52, s91, 0
	global_load_dword v12, v95, s[2:3]
	s_add_u32 s2, s78, s49
	s_addc_u32 s3, s79, s52
	global_load_dword v20, v95, s[2:3]
	s_add_u32 s2, s74, s49
	s_addc_u32 s3, s75, s52
	s_add_u32 s47, s47, 0x40070
	s_addc_u32 s49, s91, 0
	global_load_dword v13, v95, s[2:3]
	s_add_u32 s2, s78, s47
	s_addc_u32 s3, s79, s49
	global_load_dword v2, v95, s[2:3]
	s_add_u32 s2, s74, s47
	s_addc_u32 s3, s75, s49
	global_load_dword v31, v95, s[2:3]
	v_readlane_b32 s2, v254, 37
	v_readlane_b32 s10, v253, 13
	v_readlane_b32 s11, v253, 14
	v_mov_b32_e32 v22, s2
	v_readlane_b32 s2, v254, 39
	v_readlane_b32 s12, v253, 15
	v_readlane_b32 s13, v253, 16
	v_mov_b32_e32 v24, s2
	v_readlane_b32 s2, v254, 41
	v_readlane_b32 s14, v253, 17
	v_readlane_b32 s15, v253, 18
	v_mov_b32_e32 v26, s2
	s_waitcnt vmcnt(16)
	v_max_f32_e32 v33, v30, v30
	v_readlane_b32 s2, v254, 43
	v_readlane_b32 s16, v253, 19
	v_readlane_b32 s17, v253, 20
	v_mov_b32_e32 v32, s2
	v_readlane_b32 s18, v253, 21
	s_movk_i32 s18, 0x3000
	s_movk_i32 s17, 0x2000
	s_movk_i32 s16, 0x4000
	s_mov_b32 s15, s38
	s_mov_b32 s14, s28
	s_mov_b32 s13, s36
	s_waitcnt vmcnt(15)
	v_add_f32_e32 v8, 0, v8
	v_mov_b32_e32 v21, v8
	s_mov_b32 s12, s73
	s_mov_b32 s11, s72
	s_waitcnt vmcnt(13)
	v_add_f32_e32 v9, v8, v9
	v_mov_b32_e32 v14, v9
	s_mov_b32 s10, s67
	v_readlane_b32 s9, v253, 12
	v_readlane_b32 s19, v253, 22
	v_readlane_b32 s22, v253, 25
	v_readlane_b32 s23, v253, 26
	s_waitcnt vmcnt(11)
	v_add_f32_e32 v15, v9, v10
	v_mov_b32_e32 v10, v15
	s_waitcnt vmcnt(10)
	v_pk_add_f32 v[16:17], v[4:5], v[14:15] neg_lo:[0,1] neg_hi:[0,1]
	ds_write2_b32 v22, v16, v17 offset1:1
	s_waitcnt vmcnt(9)
	v_add_f32_e32 v11, v15, v11
	v_mov_b32_e32 v14, v11
	ds_write_b128 v95, v[8:11] offset:12288
	s_waitcnt vmcnt(7)
	v_add_f32_e32 v15, v11, v18
	v_mov_b32_e32 v18, v15
	v_mov_b32_e32 v4, v15
	s_waitcnt vmcnt(6)
	v_pk_add_f32 v[22:23], v[6:7], v[14:15] neg_lo:[0,1] neg_hi:[0,1]
	ds_write2_b32 v24, v22, v23 offset1:1
	s_waitcnt vmcnt(5)
	v_add_f32_e32 v14, v15, v19
	v_mov_b32_e32 v5, v14
	v_mov_b32_e32 v19, v14
	s_waitcnt vmcnt(3)
	v_add_f32_e32 v20, v14, v20
	v_mov_b32_e32 v15, v20
	v_mov_b32_e32 v6, v20
	s_waitcnt vmcnt(2)
	v_pk_add_f32 v[24:25], v[12:13], v[14:15] neg_lo:[0,1] neg_hi:[0,1]
	ds_write_b96 v95, v[4:6] offset:12304
	ds_write2_b32 v26, v24, v25 offset1:1
	s_waitcnt vmcnt(1)
	v_pk_add_f32 v[28:29], v[2:3], v[20:21] neg_lo:[0,1] neg_hi:[0,1]
	v_pk_add_f32 v[26:27], v[2:3], v[20:21]
	v_max_f32_e32 v2, v33, v29
	v_sub_f32_e32 v4, v30, v2
	v_max_f32_e32 v3, v2, v16
	v_mul_f32_e32 v5, 0x3fb8aa3b, v4
	v_max_f32_e32 v4, v3, v17
	v_sub_f32_e32 v13, v30, v3
	v_exp_f32_e32 v12, v5
	v_max_f32_e32 v5, v4, v22
	v_pk_add_f32 v[6:7], v[8:9], v[2:3]
	v_mul_f32_e32 v8, 0x3fb8aa3b, v13
	v_sub_f32_e32 v9, v30, v4
	ds_write_b128 v95, v[2:5] offset:12352
	v_sub_f32_e32 v3, v30, v5
	v_max_f32_e32 v2, v5, v23
	v_exp_f32_e32 v13, v8
	v_mul_f32_e32 v14, 0x3fb8aa3b, v9
	v_pk_add_f32 v[8:9], v[10:11], v[4:5]
	v_mul_f32_e32 v4, 0x3fb8aa3b, v3
	v_sub_f32_e32 v5, v30, v2
	v_max_f32_e32 v3, v2, v24
	s_waitcnt vmcnt(0)
	v_sub_f32_e32 v27, v31, v26
	v_exp_f32_e32 v15, v4
	v_mul_f32_e32 v5, 0x3fb8aa3b, v5
	v_max_f32_e32 v4, v3, v25
	v_exp_f32_e32 v14, v14
	ds_write_b128 v95, v[6:9] offset:12416
	v_exp_f32_e32 v8, v5
	v_max_f32_e32 v5, v4, v27
	v_sub_f32_e32 v9, v30, v3
	v_sub_f32_e32 v10, v30, v4
	v_sub_f32_e32 v11, v30, v5
	v_mul_f32_e32 v9, 0x3fb8aa3b, v9
	v_mul_f32_e32 v10, 0x3fb8aa3b, v10
	v_mul_f32_e32 v11, 0x3fb8aa3b, v11
	v_exp_f32_e32 v9, v9
	v_exp_f32_e32 v10, v10
	v_exp_f32_e32 v11, v11
	v_pk_add_f32 v[6:7], v[18:19], v[2:3]
	ds_write_b128 v95, v[12:15] offset:12384
	ds_write2_b32 v32, v26, v29 offset1:1
	ds_write_b32 v95, v27 offset:12348
	ds_write_b128 v95, v[2:5] offset:12368
	ds_write_b128 v95, v[8:11] offset:12400
	v_sub_f32_e32 v2, v29, v5
	v_mul_f32_e32 v2, 0x3fb8aa3b, v2
	v_exp_f32_e32 v12, v2
	v_sub_f32_e32 v2, v16, v5
	v_mul_f32_e32 v2, 0x3fb8aa3b, v2
	v_exp_f32_e32 v13, v2
	v_sub_f32_e32 v2, v17, v5
	v_mul_f32_e32 v2, 0x3fb8aa3b, v2
	v_exp_f32_e32 v14, v2
	v_sub_f32_e32 v2, v22, v5
	v_mul_f32_e32 v2, 0x3fb8aa3b, v2
	v_exp_f32_e32 v15, v2
	v_sub_f32_e32 v2, v23, v5
	v_mul_f32_e32 v2, 0x3fb8aa3b, v2
	v_exp_f32_e32 v16, v2
	v_sub_f32_e32 v2, v24, v5
	v_mul_f32_e32 v2, 0x3fb8aa3b, v2
	v_exp_f32_e32 v17, v2
	v_sub_f32_e32 v2, v25, v5
	v_mul_f32_e32 v2, 0x3fb8aa3b, v2
	v_exp_f32_e32 v18, v2
	v_sub_f32_e32 v2, v27, v5
	v_mul_f32_e32 v2, 0x3fb8aa3b, v2
	v_mov_b32_e32 v21, v26
	v_exp_f32_e32 v19, v2
	v_pk_add_f32 v[8:9], v[20:21], v[4:5]
	ds_write_b128 v95, v[6:9] offset:12432
	ds_write_b128 v95, v[12:15] offset:12448
	ds_write_b128 v95, v[16:19] offset:12464
	v_mov_b32_e32 v8, v11
	ds_write_b64 v95, v[8:9] offset:12480

; __device__ __forceinline__ unsigned f2bf(float f) { unsigned u = __builtin_bit_cast(unsigned, f); return (u + 0x7fffu + ((u >> 16) & 1u)) >> 16; }
; __device__ __forceinline__ float sigmoidf_(float x) { return __builtin_amdgcn_rcpf(1.f + __expf(-x)); }
; __device__ __forceinline__ float bfv(bf16 v) { return __uint_as_float((unsigned)v << 16); }
; template <int MASK> __device__ __forceinline__ void phase3(const Args& a, LAS unsigned char* lds, int tid, int wave, int lane, int vcu, int G) {
;     ...
;                 for (int t = 0; t < 8; ++t) if ((t >> 1) == qt) {
;                     float num = SC[24 + t] * cq[t], den = SC[24 + t] * SC[128 + t];
; #pragma unroll
;                     for (int s = 0; s < 8; ++s) { const float w = SC[64 + t * 8 + s]; num += w * VS[s * 128 + dv]; den += w; }
;                     const float hh = num / fmaxf(fabsf(den), __expf(-SC[32 + t]));
;                     const size_t R = NP + 8 * b + t;
;                     const float hv = hh * sigmoidf_(bfv(P1[R * P1W + C_MO + hd * 128 + dv]));
;                     HM[R * 512 + hd * 128 + dv] = (bf16)f2bf(hv); HB[t * 128 + dv] = hv;
;                 }
.LBB0_725:
	s_or_b64 exec, exec, s[68:69]
	s_lshl_b32 s52, s94, 1
	v_lshl_add_u64 v[6:7], v[100:101], 0, s[52:53]
	v_cmp_lt_i32_e32 vcc, 1, v107
	s_and_saveexec_b64 s[2:3], vcc
	s_xor_b64 s[88:89], exec, s[2:3]
	s_mov_b32 s94, s4
	s_cbranch_execz .LBB0_731
	v_cmp_lt_i32_e32 vcc, 2, v107
	s_and_saveexec_b64 s[2:3], vcc
	s_xor_b64 s[90:91], exec, s[2:3]
	s_cbranch_execz .LBB0_728
	v_add_u32_e64 v2, s18, 0
	ds_read2_b64 v[2:5], v2 offset0:15 offset1:19
	ds_read_b64 v[14:15], v95 offset:12824
	ds_read_b128 v[16:19], v95 offset:12736
	v_add_f32_e32 v20, v61, v62
	s_mul_i32 s47, s48, 0x1400
	s_waitcnt lgkmcnt(2)
	v_mul_f32_e32 v4, 0xbfb8aa3b, v4
	v_exp_f32_e32 v4, v4
	s_waitcnt lgkmcnt(0)
	v_mul_f32_e32 v22, v44, v16
	v_fmac_f32_e32 v22, v20, v2
	v_fma_f32 v2, v2, v14, v16
	v_fmac_f32_e32 v22, v45, v17
	v_add_f32_e32 v2, v2, v17
	v_fmac_f32_e32 v22, v8, v18
	v_add_f32_e32 v2, v2, v18
	v_fmac_f32_e32 v22, v9, v19
	v_add_f32_e32 v2, v2, v19
	ds_read_b128 v[16:19], v95 offset:12752
	s_add_i32 s55, s47, 0x5007800
	v_add_f32_e32 v21, v63, v64
	v_mul_f32_e32 v5, 0xbfb8aa3b, v5
	v_exp_f32_e32 v5, v5
	s_waitcnt lgkmcnt(0)
	v_add_f32_e32 v2, v2, v16
	v_fmac_f32_e32 v22, v10, v16
	v_add_f32_e32 v2, v2, v17
	v_fmac_f32_e32 v22, v11, v17
	v_add_f32_e32 v2, v2, v18
	v_fmac_f32_e32 v22, v12, v18
	v_add_f32_e32 v2, v2, v19
	v_fmac_f32_e32 v22, v13, v19
	v_max_f32_e64 v2, |v2|, v4
	v_div_scale_f32 v4, s[2:3], v2, v2, v22
	v_rcp_f32_e32 v14, v4
	s_add_i32 s2, s48, 0x4006
	s_ashr_i32 s3, s2, 31
	s_mul_hi_i32 s49, s2, 0x1400
	v_fma_f32 v16, -v4, v14, 1.0
	v_fmac_f32_e32 v14, v16, v14
	v_div_scale_f32 v16, vcc, v22, v2, v22
	v_mul_f32_e32 v17, v16, v14
	v_fma_f32 v18, -v4, v17, v16
	v_fmac_f32_e32 v17, v18, v14
	s_add_u32 s55, s56, s55
	v_fma_f32 v4, -v4, v17, v16
	s_addc_u32 s49, s57, s49
	v_div_fmas_f32 v4, v4, v14, v17
	s_add_u32 s68, s55, s52
	v_div_fixup_f32 v2, v4, v2, v22
	s_addc_u32 s69, s49, 0
	v_lshlrev_b32_e32 v4, 1, v168
	v_mov_b32_e32 v14, v190
	s_lshl_b64 s[2:3], s[2:3], 10
	v_lshl_add_u64 v[16:17], v[6:7], 0, s[2:3]
	s_add_i32 s47, s47, 0x5008c00
	s_waitcnt vmcnt(0)
	v_lshlrev_b32_e32 v14, 16, v14
	v_mul_f32_e32 v14, 0xbfb8aa3b, v14
	v_exp_f32_e32 v14, v14
	s_nop 0
	v_add_f32_e32 v14, 1.0, v14
	v_rcp_f32_e32 v14, v14
	s_nop 0
	v_mul_f32_e32 v2, v2, v14
	v_bfe_u32 v14, v2, 16, 1
	v_add3_u32 v14, v2, v14, s81
	global_store_short_d16_hi v[16:17], v14, off
	ds_read_b128 v[16:19], v95 offset:12768
	s_waitcnt lgkmcnt(0)
	v_mul_f32_e32 v20, v44, v16
	v_fmac_f32_e32 v20, v21, v3
	v_fma_f32 v3, v3, v15, v16
	v_fmac_f32_e32 v20, v45, v17
	v_add_f32_e32 v3, v3, v17
	ds_read_b128 v[14:17], v95 offset:12784
	v_add_f32_e32 v3, v3, v18
	v_fmac_f32_e32 v20, v8, v18
	v_add_f32_e32 v3, v3, v19
	v_fmac_f32_e32 v20, v9, v19
	s_waitcnt lgkmcnt(0)
	v_add_f32_e32 v3, v3, v14
	v_fmac_f32_e32 v20, v10, v14
	v_add_f32_e32 v3, v3, v15
	v_fmac_f32_e32 v20, v11, v15
	v_add_f32_e32 v3, v3, v16
	v_fmac_f32_e32 v20, v12, v16
	v_add_f32_e32 v3, v3, v17
	v_fmac_f32_e32 v20, v13, v17
	v_max_f32_e64 v3, |v3|, v5
	v_div_scale_f32 v5, s[2:3], v3, v3, v20
	v_rcp_f32_e32 v8, v5
	s_nop 0
	v_fma_f32 v9, -v5, v8, 1.0
	v_fmac_f32_e32 v8, v9, v8
	v_div_scale_f32 v9, vcc, v20, v3, v20
	v_mul_f32_e32 v10, v9, v8
	v_fma_f32 v11, -v5, v10, v9
	v_fmac_f32_e32 v10, v11, v8
	v_fma_f32 v5, -v5, v10, v9
	v_div_fmas_f32 v5, v5, v8, v10
	s_add_i32 vcc_lo, s48, 0x4007
	s_ashr_i32 vcc_hi, vcc_lo, 31
	s_mul_hi_i32 s2, vcc_lo, 0x1400
	s_add_u32 s3, s56, s47
	s_addc_u32 s2, s57, s2
	s_add_u32 s68, s3, s52
	s_addc_u32 s69, s2, 0
	v_mov_b32_e32 v4, v191
	v_div_fixup_f32 v3, v5, v3, v20
	s_lshl_b64 s[2:3], vcc, 10
	s_waitcnt vmcnt(0)
	v_lshlrev_b32_e32 v4, 16, v4
	v_mul_f32_e32 v4, 0xbfb8aa3b, v4
	v_exp_f32_e32 v4, v4
	s_nop 0
	v_add_f32_e32 v4, 1.0, v4
	v_rcp_f32_e32 v4, v4
	s_nop 0
	v_mul_f32_e32 v3, v3, v4
	v_bfe_u32 v4, v3, 16, 1
	v_add3_u32 v8, v3, v4, s81
	v_lshl_add_u64 v[4:5], v[6:7], 0, s[2:3]
	global_store_short_d16_hi v[4:5], v8, off
	ds_write2st64_b32 v218, v2, v3 offset0:64 offset1:66
; __device__ __forceinline__ unsigned f2bf(float f) { unsigned u = __builtin_bit_cast(unsigned, f); return (u + 0x7fffu + ((u >> 16) & 1u)) >> 16; }
; __device__ __forceinline__ float sigmoidf_(float x) { return __builtin_amdgcn_rcpf(1.f + __expf(-x)); }
; __device__ __forceinline__ float bfv(bf16 v) { return __uint_as_float((unsigned)v << 16); }
; template <int MASK> __device__ __forceinline__ void phase3(const Args& a, LAS unsigned char* lds, int tid, int wave, int lane, int vcu, int G) {
;     ...
;                 for (int t = 0; t < 8; ++t) if ((t >> 1) == qt) {
;                     float num = SC[24 + t] * cq[t], den = SC[24 + t] * SC[128 + t];
; #pragma unroll
;                     for (int s = 0; s < 8; ++s) { const float w = SC[64 + t * 8 + s]; num += w * VS[s * 128 + dv]; den += w; }
;                     const float hh = num / fmaxf(fabsf(den), __expf(-SC[32 + t]));
;                     const size_t R = NP + 8 * b + t;
;                     const float hv = hh * sigmoidf_(bfv(P1[R * P1W + C_MO + hd * 128 + dv]));
;                     HM[R * 512 + hd * 128 + dv] = (bf16)f2bf(hv); HB[t * 128 + dv] = hv;
;                 }
.LBB0_728:
	s_andn2_saveexec_b64 s[90:91], s[90:91]
	s_cbranch_execz .LBB0_730
	v_add_u32_e64 v2, s18, 0
	ds_read2_b64 v[2:5], v2 offset0:14 offset1:18
	ds_read_b64 v[14:15], v95 offset:12816
	ds_read_b128 v[16:19], v95 offset:12672
	v_add_f32_e32 v20, v57, v58
	s_mul_i32 s47, s48, 0x1400
	s_waitcnt lgkmcnt(2)
	v_mul_f32_e32 v4, 0xbfb8aa3b, v4
	v_exp_f32_e32 v4, v4
	s_waitcnt lgkmcnt(0)
	v_mul_f32_e32 v22, v44, v16
	v_fmac_f32_e32 v22, v20, v2
	v_fma_f32 v2, v2, v14, v16
	v_fmac_f32_e32 v22, v45, v17
	v_add_f32_e32 v2, v2, v17
	v_fmac_f32_e32 v22, v8, v18
	v_add_f32_e32 v2, v2, v18
	v_fmac_f32_e32 v22, v9, v19
	v_add_f32_e32 v2, v2, v19
	ds_read_b128 v[16:19], v95 offset:12688
	s_add_i32 s55, s47, 0x5005000
	v_add_f32_e32 v21, v59, v60
	v_mul_f32_e32 v5, 0xbfb8aa3b, v5
	v_exp_f32_e32 v5, v5
	s_waitcnt lgkmcnt(0)
	v_add_f32_e32 v2, v2, v16
	v_fmac_f32_e32 v22, v10, v16
	v_add_f32_e32 v2, v2, v17
	v_fmac_f32_e32 v22, v11, v17
	v_add_f32_e32 v2, v2, v18
	v_fmac_f32_e32 v22, v12, v18
	v_add_f32_e32 v2, v2, v19
	v_fmac_f32_e32 v22, v13, v19
	v_max_f32_e64 v2, |v2|, v4
	v_div_scale_f32 v4, s[2:3], v2, v2, v22
	v_rcp_f32_e32 v14, v4
	s_add_i32 s2, s48, 0x4004
	s_ashr_i32 s3, s2, 31
	s_mul_hi_i32 s49, s2, 0x1400
	v_fma_f32 v16, -v4, v14, 1.0
	v_fmac_f32_e32 v14, v16, v14
	v_div_scale_f32 v16, vcc, v22, v2, v22
	v_mul_f32_e32 v17, v16, v14
	v_fma_f32 v18, -v4, v17, v16
	v_fmac_f32_e32 v17, v18, v14
	s_add_u32 s55, s56, s55
	v_fma_f32 v4, -v4, v17, v16
	s_addc_u32 s49, s57, s49
	v_div_fmas_f32 v4, v4, v14, v17
	s_add_u32 s68, s55, s52
	v_div_fixup_f32 v2, v4, v2, v22
	s_addc_u32 s69, s49, 0
	v_lshlrev_b32_e32 v4, 1, v168
	v_mov_b32_e32 v14, v190
	s_lshl_b64 s[2:3], s[2:3], 10
	v_lshl_add_u64 v[16:17], v[6:7], 0, s[2:3]
	s_add_i32 s47, s47, 0x5006400
	s_waitcnt vmcnt(0)
	v_lshlrev_b32_e32 v14, 16, v14
	v_mul_f32_e32 v14, 0xbfb8aa3b, v14
	v_exp_f32_e32 v14, v14
	s_nop 0
	v_add_f32_e32 v14, 1.0, v14
	v_rcp_f32_e32 v14, v14
	s_nop 0
	v_mul_f32_e32 v2, v2, v14
	v_bfe_u32 v14, v2, 16, 1
	v_add3_u32 v14, v2, v14, s81
	global_store_short_d16_hi v[16:17], v14, off
	ds_read_b128 v[16:19], v95 offset:12704
	s_waitcnt lgkmcnt(0)
	v_mul_f32_e32 v20, v44, v16
	v_fmac_f32_e32 v20, v21, v3
	v_fma_f32 v3, v3, v15, v16
	v_fmac_f32_e32 v20, v45, v17
	v_add_f32_e32 v3, v3, v17
	ds_read_b128 v[14:17], v95 offset:12720
	v_add_f32_e32 v3, v3, v18
	v_fmac_f32_e32 v20, v8, v18
	v_add_f32_e32 v3, v3, v19
	v_fmac_f32_e32 v20, v9, v19
	s_waitcnt lgkmcnt(0)
	v_add_f32_e32 v3, v3, v14
	v_fmac_f32_e32 v20, v10, v14
	v_add_f32_e32 v3, v3, v15
	v_fmac_f32_e32 v20, v11, v15
	v_add_f32_e32 v3, v3, v16
	v_fmac_f32_e32 v20, v12, v16
	v_add_f32_e32 v3, v3, v17
	v_fmac_f32_e32 v20, v13, v17
	v_max_f32_e64 v3, |v3|, v5
	v_div_scale_f32 v5, s[2:3], v3, v3, v20
	v_rcp_f32_e32 v8, v5
	s_nop 0
	v_fma_f32 v9, -v5, v8, 1.0
	v_fmac_f32_e32 v8, v9, v8
	v_div_scale_f32 v9, vcc, v20, v3, v20
	v_mul_f32_e32 v10, v9, v8
	v_fma_f32 v11, -v5, v10, v9
	v_fmac_f32_e32 v10, v11, v8
	v_fma_f32 v5, -v5, v10, v9
	v_div_fmas_f32 v5, v5, v8, v10
	s_add_i32 vcc_lo, s48, 0x4005
	s_ashr_i32 vcc_hi, vcc_lo, 31
	s_mul_hi_i32 s2, vcc_lo, 0x1400
	s_add_u32 s3, s56, s47
	s_addc_u32 s2, s57, s2
	s_add_u32 s68, s3, s52
	s_addc_u32 s69, s2, 0
	v_mov_b32_e32 v4, v191
	v_div_fixup_f32 v3, v5, v3, v20
	s_lshl_b64 s[2:3], vcc, 10
	s_waitcnt vmcnt(0)
	v_lshlrev_b32_e32 v4, 16, v4
	v_mul_f32_e32 v4, 0xbfb8aa3b, v4
	v_exp_f32_e32 v4, v4
	s_nop 0
	v_add_f32_e32 v4, 1.0, v4
	v_rcp_f32_e32 v4, v4
	s_nop 0
	v_mul_f32_e32 v3, v3, v4
	v_bfe_u32 v4, v3, 16, 1
	v_add3_u32 v8, v3, v4, s81
	v_lshl_add_u64 v[4:5], v[6:7], 0, s[2:3]
	global_store_short_d16_hi v[4:5], v8, off
	ds_write2st64_b32 v218, v2, v3 offset0:60 offset1:62

; __device__ __forceinline__ unsigned f2bf(float f) { unsigned u = __builtin_bit_cast(unsigned, f); return (u + 0x7fffu + ((u >> 16) & 1u)) >> 16; }
; __device__ __forceinline__ float sigmoidf_(float x) { return __builtin_amdgcn_rcpf(1.f + __expf(-x)); }
; __device__ __forceinline__ float bfv(bf16 v) { return __uint_as_float((unsigned)v << 16); }
; template <int MASK> __device__ __forceinline__ void phase3(const Args& a, LAS unsigned char* lds, int tid, int wave, int lane, int vcu, int G) {
;     ...
;                 for (int t = 0; t < 8; ++t) if ((t >> 1) == qt) {
;                     float num = SC[24 + t] * cq[t], den = SC[24 + t] * SC[128 + t];
; #pragma unroll
;                     for (int s = 0; s < 8; ++s) { const float w = SC[64 + t * 8 + s]; num += w * VS[s * 128 + dv]; den += w; }
;                     const float hh = num / fmaxf(fabsf(den), __expf(-SC[32 + t]));
;                     const size_t R = NP + 8 * b + t;
;                     const float hv = hh * sigmoidf_(bfv(P1[R * P1W + C_MO + hd * 128 + dv]));
;                     HM[R * 512 + hd * 128 + dv] = (bf16)f2bf(hv); HB[t * 128 + dv] = hv;
;                 }
.LBB0_731:
	s_andn2_saveexec_b64 s[88:89], s[88:89]
	s_cbranch_execz .LBB0_737
	v_cmp_ne_u32_e32 vcc, 1, v107
	v_add_u32_e64 v2, s18, 0
	v_lshlrev_b32_e32 v16, 1, v168
	s_and_saveexec_b64 s[2:3], vcc
	s_xor_b64 s[90:91], exec, s[2:3]
	s_cbranch_execz .LBB0_734
	ds_read2_b64 v[2:5], v2 offset0:12 offset1:16
	ds_read_b64 v[14:15], v95 offset:12800
	ds_read_b128 v[18:21], v95 offset:12544
	v_add_f32_e32 v17, v49, v50
	s_ashr_i32 s55, s54, 31
	s_waitcnt lgkmcnt(2)
	v_mul_f32_e32 v4, 0xbfb8aa3b, v4
	v_exp_f32_e32 v4, v4
	s_waitcnt lgkmcnt(0)
	v_mul_f32_e32 v23, v44, v18
	v_fmac_f32_e32 v23, v17, v2
	v_fma_f32 v2, v2, v14, v18
	v_fmac_f32_e32 v23, v45, v19
	v_add_f32_e32 v2, v2, v19
	v_fmac_f32_e32 v23, v8, v20
	v_add_f32_e32 v2, v2, v20
	v_fmac_f32_e32 v23, v9, v21
	v_add_f32_e32 v2, v2, v21
	ds_read_b128 v[18:21], v95 offset:12560
	v_add_f32_e32 v22, v51, v52
	v_mul_f32_e32 v5, 0xbfb8aa3b, v5
	v_exp_f32_e32 v5, v5
	s_waitcnt lgkmcnt(0)
	v_add_f32_e32 v2, v2, v18
	v_fmac_f32_e32 v23, v10, v18
	v_add_f32_e32 v2, v2, v19
	v_fmac_f32_e32 v23, v11, v19
	v_add_f32_e32 v2, v2, v20
	v_fmac_f32_e32 v23, v12, v20
	v_add_f32_e32 v2, v2, v21
	v_fmac_f32_e32 v23, v13, v21
	v_max_f32_e64 v2, |v2|, v4
	v_div_scale_f32 v4, s[2:3], v2, v2, v23
	v_rcp_f32_e32 v14, v4
	s_mul_i32 s3, s54, 0x1400
	s_mul_hi_i32 s2, s54, 0x1400
	s_add_u32 s3, s56, s3
	v_fma_f32 v17, -v4, v14, 1.0
	v_fmac_f32_e32 v14, v17, v14
	v_div_scale_f32 v17, vcc, v23, v2, v23
	v_mul_f32_e32 v18, v17, v14
	v_fma_f32 v19, -v4, v18, v17
	v_fmac_f32_e32 v18, v19, v14
	s_addc_u32 s47, s57, s2
	v_fma_f32 v4, -v4, v18, v17
	s_add_u32 s2, s3, s52
	v_div_fmas_f32 v4, v4, v14, v18
	s_addc_u32 s3, s47, 0
	v_div_fixup_f32 v2, v4, v2, v23
	v_mov_b32_e32 v4, v190
	s_lshl_b64 s[2:3], s[54:55], 10
	v_lshl_add_u64 v[18:19], v[6:7], 0, s[2:3]
	s_add_i32 s54, s48, 0x4001
	s_ashr_i32 s55, s54, 31
	s_waitcnt vmcnt(0)
	v_lshlrev_b32_e32 v4, 16, v4
	v_mul_f32_e32 v4, 0xbfb8aa3b, v4
	v_exp_f32_e32 v4, v4
	s_nop 0
	v_add_f32_e32 v4, 1.0, v4
	v_rcp_f32_e32 v4, v4
	s_nop 0
	v_mul_f32_e32 v2, v2, v4
	v_bfe_u32 v4, v2, 16, 1
	v_add3_u32 v4, v2, v4, s81
	global_store_short_d16_hi v[18:19], v4, off
	ds_read_b128 v[18:21], v95 offset:12576
	s_waitcnt lgkmcnt(0)
	v_mul_f32_e32 v4, v44, v18
	v_fmac_f32_e32 v4, v22, v3
	v_fma_f32 v3, v3, v15, v18
	v_fmac_f32_e32 v4, v45, v19
	v_add_f32_e32 v3, v3, v19
	v_fmac_f32_e32 v4, v8, v20
	v_add_f32_e32 v3, v3, v20
	v_fmac_f32_e32 v4, v9, v21
	v_add_f32_e32 v3, v3, v21
	ds_read_b128 v[18:21], v95 offset:12592
	s_waitcnt lgkmcnt(0)
	v_add_f32_e32 v3, v3, v18
	v_fmac_f32_e32 v4, v10, v18
	v_add_f32_e32 v3, v3, v19
	v_fmac_f32_e32 v4, v11, v19
	v_add_f32_e32 v3, v3, v20
	v_fmac_f32_e32 v4, v12, v20
	v_add_f32_e32 v3, v3, v21
	v_fmac_f32_e32 v4, v13, v21
	v_max_f32_e64 v3, |v3|, v5
	v_div_scale_f32 v5, s[2:3], v3, v3, v4
	v_rcp_f32_e32 v8, v5
	s_mul_i32 s3, s54, 0x1400
	s_mul_hi_i32 s2, s54, 0x1400
	s_add_u32 s3, s56, s3
	v_fma_f32 v9, -v5, v8, 1.0
	v_fmac_f32_e32 v8, v9, v8
	v_div_scale_f32 v9, vcc, v4, v3, v4
	v_mul_f32_e32 v10, v9, v8
	v_fma_f32 v11, -v5, v10, v9
	v_fmac_f32_e32 v10, v11, v8
	v_fma_f32 v5, -v5, v10, v9
	s_addc_u32 s2, s57, s2
	v_div_fmas_f32 v5, v5, v8, v10
	s_add_u32 vcc_lo, s3, s52
	s_addc_u32 vcc_hi, s2, 0
	v_div_fixup_f32 v3, v5, v3, v4
	v_mov_b32_e32 v4, v191
	s_lshl_b64 s[2:3], s[54:55], 10
	s_waitcnt vmcnt(0)
	v_lshlrev_b32_e32 v4, 16, v4
	v_mul_f32_e32 v4, 0xbfb8aa3b, v4
	v_exp_f32_e32 v4, v4
	s_nop 0
	v_add_f32_e32 v4, 1.0, v4
	v_rcp_f32_e32 v4, v4
	s_nop 0
	v_mul_f32_e32 v3, v3, v4
	v_bfe_u32 v4, v3, 16, 1
	v_add3_u32 v8, v3, v4, s81
	v_lshl_add_u64 v[4:5], v[6:7], 0, s[2:3]
	global_store_short_d16_hi v[4:5], v8, off
	ds_write2st64_b32 v218, v2, v3 offset0:52 offset1:54
; __device__ __forceinline__ unsigned f2bf(float f) { unsigned u = __builtin_bit_cast(unsigned, f); return (u + 0x7fffu + ((u >> 16) & 1u)) >> 16; }
; __device__ __forceinline__ float sigmoidf_(float x) { return __builtin_amdgcn_rcpf(1.f + __expf(-x)); }
; __device__ __forceinline__ float bfv(bf16 v) { return __uint_as_float((unsigned)v << 16); }
; template <int MASK> __device__ __forceinline__ void phase3(const Args& a, LAS unsigned char* lds, int tid, int wave, int lane, int vcu, int G) {
;     ...
;                 for (int t = 0; t < 8; ++t) if ((t >> 1) == qt) {
;                     float num = SC[24 + t] * cq[t], den = SC[24 + t] * SC[128 + t];
; #pragma unroll
;                     for (int s = 0; s < 8; ++s) { const float w = SC[64 + t * 8 + s]; num += w * VS[s * 128 + dv]; den += w; }
;                     const float hh = num / fmaxf(fabsf(den), __expf(-SC[32 + t]));
;                     const size_t R = NP + 8 * b + t;
;                     const float hv = hh * sigmoidf_(bfv(P1[R * P1W + C_MO + hd * 128 + dv]));
;                     HM[R * 512 + hd * 128 + dv] = (bf16)f2bf(hv); HB[t * 128 + dv] = hv;
;                 }
.LBB0_734:
	s_andn2_saveexec_b64 s[54:55], s[90:91]
	s_cbranch_execz .LBB0_736
	ds_read2_b64 v[2:5], v2 offset0:13 offset1:17
	ds_read_b64 v[14:15], v95 offset:12808
	ds_read_b128 v[18:21], v95 offset:12608
	v_add_f32_e32 v17, v53, v54
	s_mul_i32 s47, s48, 0x1400
	s_waitcnt lgkmcnt(2)
	v_mul_f32_e32 v4, 0xbfb8aa3b, v4
	v_exp_f32_e32 v4, v4
	s_waitcnt lgkmcnt(0)
	v_mul_f32_e32 v23, v44, v18
	v_fmac_f32_e32 v23, v17, v2
	v_fma_f32 v2, v2, v14, v18
	v_fmac_f32_e32 v23, v45, v19
	v_add_f32_e32 v2, v2, v19
	v_fmac_f32_e32 v23, v8, v20
	v_add_f32_e32 v2, v2, v20
	v_fmac_f32_e32 v23, v9, v21
	v_add_f32_e32 v2, v2, v21
	ds_read_b128 v[18:21], v95 offset:12624
	s_add_i32 s68, s47, 0x5002800
	v_add_f32_e32 v22, v55, v56
	v_mul_f32_e32 v5, 0xbfb8aa3b, v5
	v_exp_f32_e32 v5, v5
	s_waitcnt lgkmcnt(0)
	v_add_f32_e32 v2, v2, v18
	v_fmac_f32_e32 v23, v10, v18
	v_add_f32_e32 v2, v2, v19
	v_fmac_f32_e32 v23, v11, v19
	v_add_f32_e32 v2, v2, v20
	v_fmac_f32_e32 v23, v12, v20
	v_add_f32_e32 v2, v2, v21
	v_fmac_f32_e32 v23, v13, v21
	v_max_f32_e64 v2, |v2|, v4
	v_div_scale_f32 v4, s[2:3], v2, v2, v23
	v_rcp_f32_e32 v14, v4
	s_add_i32 s2, s48, 0x4002
	s_ashr_i32 s3, s2, 31
	s_mul_hi_i32 s49, s2, 0x1400
	v_fma_f32 v17, -v4, v14, 1.0
	v_fmac_f32_e32 v14, v17, v14
	v_div_scale_f32 v17, vcc, v23, v2, v23
	v_mul_f32_e32 v18, v17, v14
	v_fma_f32 v19, -v4, v18, v17
	s_add_u32 s68, s56, s68
	v_fmac_f32_e32 v18, v19, v14
	s_addc_u32 s49, s57, s49
	v_fma_f32 v4, -v4, v18, v17
	s_add_u32 s68, s68, s52
	v_div_fmas_f32 v4, v4, v14, v18
	s_addc_u32 s69, s49, 0
	v_div_fixup_f32 v2, v4, v2, v23
	v_mov_b32_e32 v4, v190
	s_lshl_b64 s[2:3], s[2:3], 10
	v_lshl_add_u64 v[18:19], v[6:7], 0, s[2:3]
	s_add_i32 s90, s48, 0x4003
	s_ashr_i32 s91, s90, 31
	s_add_i32 s47, s47, 0x5003c00
	s_waitcnt vmcnt(0)
	v_lshlrev_b32_e32 v4, 16, v4
	v_mul_f32_e32 v4, 0xbfb8aa3b, v4
	v_exp_f32_e32 v4, v4
	s_nop 0
	v_add_f32_e32 v4, 1.0, v4
	v_rcp_f32_e32 v4, v4
	s_nop 0
	v_mul_f32_e32 v2, v2, v4
	v_bfe_u32 v4, v2, 16, 1
	v_add3_u32 v4, v2, v4, s81
	global_store_short_d16_hi v[18:19], v4, off
	ds_read_b128 v[18:21], v95 offset:12640
	s_waitcnt lgkmcnt(0)
	v_mul_f32_e32 v4, v44, v18
	v_fmac_f32_e32 v4, v22, v3
	v_fma_f32 v3, v3, v15, v18
	v_fmac_f32_e32 v4, v45, v19
	v_add_f32_e32 v3, v3, v19
	v_fmac_f32_e32 v4, v8, v20
	v_add_f32_e32 v3, v3, v20
	v_fmac_f32_e32 v4, v9, v21
	v_add_f32_e32 v3, v3, v21
	ds_read_b128 v[18:21], v95 offset:12656
	s_waitcnt lgkmcnt(0)
	v_add_f32_e32 v3, v3, v18
	v_fmac_f32_e32 v4, v10, v18
	v_add_f32_e32 v3, v3, v19
	v_fmac_f32_e32 v4, v11, v19
	v_add_f32_e32 v3, v3, v20
	v_fmac_f32_e32 v4, v12, v20
	v_add_f32_e32 v3, v3, v21
	v_fmac_f32_e32 v4, v13, v21
	v_max_f32_e64 v3, |v3|, v5
	v_div_scale_f32 v5, s[2:3], v3, v3, v4
	v_rcp_f32_e32 v8, v5
	s_mul_hi_i32 s2, s90, 0x1400
	s_add_u32 s3, s56, s47
	s_addc_u32 s2, s57, s2
	v_fma_f32 v9, -v5, v8, 1.0
	v_fmac_f32_e32 v8, v9, v8
	v_div_scale_f32 v9, vcc, v4, v3, v4
	v_mul_f32_e32 v10, v9, v8
	v_fma_f32 v11, -v5, v10, v9
	v_fmac_f32_e32 v10, v11, v8
	v_fma_f32 v5, -v5, v10, v9
	s_add_u32 s68, s3, s52
	v_div_fmas_f32 v5, v5, v8, v10
	s_addc_u32 s69, s2, 0
	v_div_fixup_f32 v3, v5, v3, v4
	v_mov_b32_e32 v4, v191
	s_lshl_b64 s[2:3], s[90:91], 10
	s_waitcnt vmcnt(0)
	v_lshlrev_b32_e32 v4, 16, v4
	v_mul_f32_e32 v4, 0xbfb8aa3b, v4
	v_exp_f32_e32 v4, v4
	s_nop 0
	v_add_f32_e32 v4, 1.0, v4
	v_rcp_f32_e32 v4, v4
	s_nop 0
	v_mul_f32_e32 v3, v3, v4
	v_bfe_u32 v4, v3, 16, 1
	v_add3_u32 v8, v3, v4, s81
	v_lshl_add_u64 v[4:5], v[6:7], 0, s[2:3]
	global_store_short_d16_hi v[4:5], v8, off
	ds_write2st64_b32 v218, v2, v3 offset0:56 offset1:58
